# EpiY epilogues: hoist gate/merged loads (prefetch into dead fragment regs), counted vmcnt instead of 16x serialized vmcnt(0)
# speedup vs baseline: 1.0112x; 1.0112x over previous
.LBB0_208:
	v_lshl_add_u32 v144, s52, 8, v148
	v_lshl_or_b32 v140, s51, 8, v170
	v_ashrrev_i32_e32 v145, 31, v144
	v_readlane_b32 s0, v253, 50
	v_ashrrev_i32_e32 v141, 31, v140
	v_lshlrev_b64 v[142:143], 13, v[144:145]
	v_readlane_b32 s1, v253, 51
	v_readlane_b32 s2, v254, 1
	v_readlane_b32 s3, v254, 2
	v_lshl_add_u64 v[174:175], s[0:1], 0, v[142:143]
	v_lshlrev_b64 v[142:143], 1, v[140:141]
	v_lshl_add_u64 v[140:141], v[174:175], 0, v[142:143]
	v_lshl_add_u32 v180, v144, 13, v142
	global_load_dwordx4 v[190:193], v180, s[0:1]
	v_add_u32_e32 v181, 0x20000, v180
	global_load_dwordx4 v[194:197], v181, s[0:1]
	v_add_u32_e32 v181, 0x40000, v180
	global_load_dwordx4 v[198:201], v181, s[0:1]
	v_add_u32_e32 v181, 0x60000, v180
	global_load_dwordx4 v[202:205], v181, s[0:1]
	v_add_u32_e32 v181, 0x100000, v180
	global_load_dwordx4 v[206:209], v181, s[0:1]
	v_add_u32_e32 v181, 0x120000, v180
	global_load_dwordx4 v[210:213], v181, s[0:1]
	v_add_u32_e32 v181, 0x140000, v180
	global_load_dwordx4 v[214:217], v181, s[0:1]
	v_add_u32_e32 v181, 0x160000, v180
	global_load_dwordx4 v[218:221], v181, s[0:1]
	global_load_dwordx4 v[222:225], v180, s[0:1] offset:256
	v_add_u32_e32 v181, 0x20000, v180
	global_load_dwordx4 v[226:229], v181, s[0:1] offset:256
	v_add_u32_e32 v181, 0x40000, v180
	global_load_dwordx4 v[230:233], v181, s[0:1] offset:256
	v_add_u32_e32 v181, 0x60000, v180
	global_load_dwordx4 v[234:237], v181, s[0:1] offset:256
	v_add_u32_e32 v181, 0x100000, v180
	global_load_dwordx4 v[238:241], v181, s[0:1] offset:256
	v_add_u32_e32 v181, 0x120000, v180
	global_load_dwordx4 v[242:245], v181, s[0:1] offset:256
	s_and_b64 vcc, exec, s[40:41]
	s_waitcnt vmcnt(13)
	s_nop 1
	v_mov_b32_e32 v174, v190
	v_mov_b32_e32 v175, v191
	v_mov_b32_e32 v176, v192
	v_mov_b32_e32 v177, v193
	v_lshl_add_u32 v180, v144, 13, v142
	v_add_u32_e32 v180, 0x140000, v180
	global_load_dwordx4 v[190:193], v180, s[0:1] offset:256
	v_lshlrev_b32_e32 v180, 16, v174
	v_and_b32_e32 v181, 0xffff0000, v174
	v_lshlrev_b32_e32 v174, 16, v175
	v_and_b32_e32 v175, 0xffff0000, v175
	v_pk_mul_f32 v[128:129], v[128:129], v[174:175]
	v_lshlrev_b32_e32 v174, 16, v176
	v_and_b32_e32 v175, 0xffff0000, v176
	v_pk_mul_f32 v[126:127], v[126:127], v[180:181]
	v_pk_mul_f32 v[122:123], v[122:123], v[174:175]
	v_lshlrev_b32_e32 v174, 16, v177
	v_and_b32_e32 v175, 0xffff0000, v177
	v_pk_mul_f32 v[174:175], v[124:125], v[174:175]
	v_cvt_pk_bf16_f32 v124, v126, v127
	v_cvt_pk_bf16_f32 v126, v122, v123
	v_lshlrev_b64 v[122:123], 12, v[144:145]
	v_cvt_pk_bf16_f32 v127, v174, v175
	v_lshl_add_u64 v[122:123], s[2:3], 0, v[122:123]
	v_or_b32_e32 v174, 16, v144
	v_cvt_pk_bf16_f32 v125, v128, v129
	v_lshl_add_u64 v[122:123], v[122:123], 0, v[142:143]
	v_ashrrev_i32_e32 v175, 31, v174
	global_store_dwordx4 v[122:123], v[124:127], off
	s_nop 1
	v_lshlrev_b64 v[124:125], 13, v[174:175]
	v_lshl_add_u64 v[124:125], s[0:1], 0, v[124:125]
	v_lshl_add_u64 v[124:125], v[124:125], 0, v[142:143]
	s_waitcnt vmcnt(14)
	s_nop 1
	v_mov_b32_e32 v126, v194
	v_mov_b32_e32 v127, v195
	v_mov_b32_e32 v128, v196
	v_mov_b32_e32 v129, v197
	v_lshl_add_u32 v176, v144, 13, v142
	v_add_u32_e32 v176, 0x160000, v176
	global_load_dwordx4 v[194:197], v176, s[0:1] offset:256
	v_lshlrev_b32_e32 v176, 16, v126
	v_and_b32_e32 v177, 0xffff0000, v126
	v_lshlrev_b32_e32 v126, 16, v127
	v_and_b32_e32 v127, 0xffff0000, v127
	v_pk_mul_f32 v[120:121], v[120:121], v[126:127]
	v_lshlrev_b32_e32 v126, 16, v128
	v_and_b32_e32 v127, 0xffff0000, v128
	v_pk_mul_f32 v[118:119], v[118:119], v[176:177]
	v_pk_mul_f32 v[114:115], v[114:115], v[126:127]
	v_lshlrev_b32_e32 v126, 16, v129
	v_and_b32_e32 v127, 0xffff0000, v129
	v_pk_mul_f32 v[126:127], v[116:117], v[126:127]
	v_cvt_pk_bf16_f32 v116, v118, v119
	v_cvt_pk_bf16_f32 v118, v114, v115
	v_lshlrev_b64 v[114:115], 12, v[174:175]
	v_cvt_pk_bf16_f32 v119, v126, v127
	v_lshl_add_u64 v[114:115], s[2:3], 0, v[114:115]
	v_or_b32_e32 v126, 32, v144
	v_cvt_pk_bf16_f32 v117, v120, v121
	v_lshl_add_u64 v[114:115], v[114:115], 0, v[142:143]
	v_ashrrev_i32_e32 v127, 31, v126
	global_store_dwordx4 v[114:115], v[116:119], off
	s_nop 1
	v_lshlrev_b64 v[116:117], 13, v[126:127]
	v_lshl_add_u64 v[116:117], s[0:1], 0, v[116:117]
	v_lshl_add_u64 v[116:117], v[116:117], 0, v[142:143]
	s_waitcnt vmcnt(15)
	s_nop 1
	v_mov_b32_e32 v118, v198
	v_mov_b32_e32 v119, v199
	v_mov_b32_e32 v120, v200
	v_mov_b32_e32 v121, v201
	v_lshlrev_b32_e32 v128, 16, v118
	v_and_b32_e32 v129, 0xffff0000, v118
	v_lshlrev_b32_e32 v118, 16, v119
	v_and_b32_e32 v119, 0xffff0000, v119
	v_pk_mul_f32 v[112:113], v[112:113], v[118:119]
	v_lshlrev_b32_e32 v118, 16, v120
	v_and_b32_e32 v119, 0xffff0000, v120
	v_pk_mul_f32 v[110:111], v[110:111], v[128:129]
	v_pk_mul_f32 v[106:107], v[106:107], v[118:119]
	v_lshlrev_b32_e32 v118, 16, v121
	v_and_b32_e32 v119, 0xffff0000, v121
	v_pk_mul_f32 v[118:119], v[108:109], v[118:119]
	v_cvt_pk_bf16_f32 v108, v110, v111
	v_cvt_pk_bf16_f32 v110, v106, v107
	v_lshlrev_b64 v[106:107], 12, v[126:127]
	v_cvt_pk_bf16_f32 v111, v118, v119
	v_lshl_add_u64 v[106:107], s[2:3], 0, v[106:107]
	v_or_b32_e32 v118, 48, v144
	v_cvt_pk_bf16_f32 v109, v112, v113
	v_lshl_add_u64 v[106:107], v[106:107], 0, v[142:143]
	v_ashrrev_i32_e32 v119, 31, v118
	global_store_dwordx4 v[106:107], v[108:111], off
	s_nop 1
	v_lshlrev_b64 v[108:109], 13, v[118:119]
	v_lshl_add_u64 v[108:109], s[0:1], 0, v[108:109]
	v_lshl_add_u64 v[108:109], v[108:109], 0, v[142:143]
	s_waitcnt vmcnt(15)
	s_nop 1
	v_mov_b32_e32 v110, v202
	v_mov_b32_e32 v111, v203
	v_mov_b32_e32 v112, v204
	v_mov_b32_e32 v113, v205
	v_lshlrev_b32_e32 v120, 16, v110
	v_and_b32_e32 v121, 0xffff0000, v110
	v_lshlrev_b32_e32 v110, 16, v111
	v_and_b32_e32 v111, 0xffff0000, v111
	v_pk_mul_f32 v[104:105], v[104:105], v[110:111]
	v_lshlrev_b32_e32 v110, 16, v112
	v_and_b32_e32 v111, 0xffff0000, v112
	v_pk_mul_f32 v[102:103], v[102:103], v[120:121]
	v_pk_mul_f32 v[98:99], v[98:99], v[110:111]
	v_lshlrev_b32_e32 v110, 16, v113
	v_and_b32_e32 v111, 0xffff0000, v113
	v_pk_mul_f32 v[110:111], v[100:101], v[110:111]
	v_cvt_pk_bf16_f32 v100, v102, v103
	v_cvt_pk_bf16_f32 v102, v98, v99
	v_lshlrev_b64 v[98:99], 12, v[118:119]
	v_cvt_pk_bf16_f32 v103, v110, v111
	v_lshl_add_u64 v[98:99], s[2:3], 0, v[98:99]
	v_add_u32_e32 v110, 0x80, v144
	v_cvt_pk_bf16_f32 v101, v104, v105
	v_lshl_add_u64 v[98:99], v[98:99], 0, v[142:143]
	v_ashrrev_i32_e32 v111, 31, v110
	global_store_dwordx4 v[98:99], v[100:103], off
	s_nop 1
	v_lshlrev_b64 v[100:101], 13, v[110:111]
	v_lshl_add_u64 v[100:101], s[0:1], 0, v[100:101]
	v_lshl_add_u64 v[100:101], v[100:101], 0, v[142:143]
	s_waitcnt vmcnt(15)
	s_nop 1
	v_mov_b32_e32 v102, v206
	v_mov_b32_e32 v103, v207
	v_mov_b32_e32 v104, v208
	v_mov_b32_e32 v105, v209
	v_lshlrev_b32_e32 v112, 16, v102
	v_and_b32_e32 v113, 0xffff0000, v102
	v_lshlrev_b32_e32 v102, 16, v103
	v_and_b32_e32 v103, 0xffff0000, v103
	v_pk_mul_f32 v[96:97], v[96:97], v[102:103]
	v_lshlrev_b32_e32 v102, 16, v104
	v_and_b32_e32 v103, 0xffff0000, v104
	v_pk_mul_f32 v[94:95], v[94:95], v[112:113]
	v_pk_mul_f32 v[90:91], v[90:91], v[102:103]
	v_lshlrev_b32_e32 v102, 16, v105
	v_and_b32_e32 v103, 0xffff0000, v105
	v_pk_mul_f32 v[102:103], v[92:93], v[102:103]
	v_cvt_pk_bf16_f32 v92, v94, v95
	v_cvt_pk_bf16_f32 v94, v90, v91
	v_lshlrev_b64 v[90:91], 12, v[110:111]
	v_cvt_pk_bf16_f32 v95, v102, v103
	v_lshl_add_u64 v[90:91], s[2:3], 0, v[90:91]
	v_add_u32_e32 v102, 0x90, v144
	v_cvt_pk_bf16_f32 v93, v96, v97
	v_lshl_add_u64 v[90:91], v[90:91], 0, v[142:143]
	v_ashrrev_i32_e32 v103, 31, v102
	global_store_dwordx4 v[90:91], v[92:95], off
	s_nop 1
	v_lshlrev_b64 v[92:93], 13, v[102:103]
	v_lshl_add_u64 v[92:93], s[0:1], 0, v[92:93]
	v_lshl_add_u64 v[92:93], v[92:93], 0, v[142:143]
	s_waitcnt vmcnt(15)
	s_nop 1
	v_mov_b32_e32 v94, v210
	v_mov_b32_e32 v95, v211
	v_mov_b32_e32 v96, v212
	v_mov_b32_e32 v97, v213
	v_lshlrev_b32_e32 v104, 16, v94
	v_and_b32_e32 v105, 0xffff0000, v94
	v_lshlrev_b32_e32 v94, 16, v95
	v_and_b32_e32 v95, 0xffff0000, v95
	v_pk_mul_f32 v[88:89], v[88:89], v[94:95]
	v_lshlrev_b32_e32 v94, 16, v96
	v_and_b32_e32 v95, 0xffff0000, v96
	v_pk_mul_f32 v[86:87], v[86:87], v[104:105]
	v_pk_mul_f32 v[82:83], v[82:83], v[94:95]
	v_lshlrev_b32_e32 v94, 16, v97
	v_and_b32_e32 v95, 0xffff0000, v97
	v_pk_mul_f32 v[94:95], v[84:85], v[94:95]
	v_cvt_pk_bf16_f32 v84, v86, v87
	v_cvt_pk_bf16_f32 v86, v82, v83
	v_lshlrev_b64 v[82:83], 12, v[102:103]
	v_cvt_pk_bf16_f32 v87, v94, v95
	v_lshl_add_u64 v[82:83], s[2:3], 0, v[82:83]
	v_add_u32_e32 v94, 0xa0, v144
	v_cvt_pk_bf16_f32 v85, v88, v89
	v_lshl_add_u64 v[82:83], v[82:83], 0, v[142:143]
	v_ashrrev_i32_e32 v95, 31, v94
	global_store_dwordx4 v[82:83], v[84:87], off
	s_nop 1
	v_lshlrev_b64 v[84:85], 13, v[94:95]
	v_lshl_add_u64 v[84:85], s[0:1], 0, v[84:85]
	v_lshl_add_u64 v[84:85], v[84:85], 0, v[142:143]
	s_waitcnt vmcnt(15)
	s_nop 1
	v_mov_b32_e32 v86, v214
	v_mov_b32_e32 v87, v215
	v_mov_b32_e32 v88, v216
	v_mov_b32_e32 v89, v217
	v_lshlrev_b32_e32 v96, 16, v86
	v_and_b32_e32 v97, 0xffff0000, v86
	v_lshlrev_b32_e32 v86, 16, v87
	v_and_b32_e32 v87, 0xffff0000, v87
	v_pk_mul_f32 v[80:81], v[80:81], v[86:87]
	v_lshlrev_b32_e32 v86, 16, v88
	v_and_b32_e32 v87, 0xffff0000, v88
	v_pk_mul_f32 v[78:79], v[78:79], v[96:97]
	v_pk_mul_f32 v[74:75], v[74:75], v[86:87]
	v_lshlrev_b32_e32 v86, 16, v89
	v_and_b32_e32 v87, 0xffff0000, v89
	v_pk_mul_f32 v[86:87], v[76:77], v[86:87]
	v_cvt_pk_bf16_f32 v76, v78, v79
	v_cvt_pk_bf16_f32 v78, v74, v75
	v_lshlrev_b64 v[74:75], 12, v[94:95]
	v_cvt_pk_bf16_f32 v79, v86, v87
	v_lshl_add_u64 v[74:75], s[2:3], 0, v[74:75]
	v_add_u32_e32 v86, 0xb0, v144
	v_cvt_pk_bf16_f32 v77, v80, v81
	v_lshl_add_u64 v[74:75], v[74:75], 0, v[142:143]
	v_ashrrev_i32_e32 v87, 31, v86
	global_store_dwordx4 v[74:75], v[76:79], off
	s_nop 1
	v_lshlrev_b64 v[76:77], 13, v[86:87]
	v_lshl_add_u64 v[76:77], s[0:1], 0, v[76:77]
	v_lshl_add_u64 v[76:77], v[76:77], 0, v[142:143]
	s_mov_b64 s[0:1], -1
	s_waitcnt vmcnt(15)
	s_nop 1
	v_mov_b32_e32 v78, v218
	v_mov_b32_e32 v79, v219
	v_mov_b32_e32 v80, v220
	v_mov_b32_e32 v81, v221
	v_lshlrev_b32_e32 v88, 16, v78
	v_and_b32_e32 v89, 0xffff0000, v78
	v_lshlrev_b32_e32 v78, 16, v79
	v_and_b32_e32 v79, 0xffff0000, v79
	v_pk_mul_f32 v[72:73], v[72:73], v[78:79]
	v_lshlrev_b32_e32 v78, 16, v80
	v_and_b32_e32 v79, 0xffff0000, v80
	v_pk_mul_f32 v[70:71], v[70:71], v[88:89]
	v_pk_mul_f32 v[66:67], v[66:67], v[78:79]
	v_lshlrev_b32_e32 v78, 16, v81
	v_and_b32_e32 v79, 0xffff0000, v81
	v_pk_mul_f32 v[78:79], v[68:69], v[78:79]
	v_cvt_pk_bf16_f32 v68, v70, v71
	v_cvt_pk_bf16_f32 v70, v66, v67
	v_lshlrev_b64 v[66:67], 12, v[86:87]
	v_lshl_add_u64 v[66:67], s[2:3], 0, v[66:67]
	v_cvt_pk_bf16_f32 v69, v72, v73
	v_cvt_pk_bf16_f32 v71, v78, v79
	v_lshl_add_u64 v[66:67], v[66:67], 0, v[142:143]
	global_store_dwordx4 v[66:67], v[68:71], off
	s_waitcnt vmcnt(15)
	s_nop 1
	v_mov_b32_e32 v68, v222
	v_mov_b32_e32 v69, v223
	v_mov_b32_e32 v70, v224
	v_mov_b32_e32 v71, v225
	v_lshlrev_b32_e32 v72, 16, v68
	v_and_b32_e32 v73, 0xffff0000, v68
	v_lshlrev_b32_e32 v68, 16, v69
	v_and_b32_e32 v69, 0xffff0000, v69
	v_pk_mul_f32 v[64:65], v[64:65], v[68:69]
	v_lshlrev_b32_e32 v68, 16, v70
	v_and_b32_e32 v69, 0xffff0000, v70
	v_pk_mul_f32 v[68:69], v[58:59], v[68:69]
	v_lshlrev_b32_e32 v58, 16, v71
	v_and_b32_e32 v59, 0xffff0000, v71
	v_pk_mul_f32 v[62:63], v[62:63], v[72:73]
	v_pk_mul_f32 v[70:71], v[60:61], v[58:59]
	v_cvt_pk_bf16_f32 v58, v62, v63
	v_cvt_pk_bf16_f32 v59, v64, v65
	v_cvt_pk_bf16_f32 v60, v68, v69
	v_cvt_pk_bf16_f32 v61, v70, v71
	global_store_dwordx4 v[122:123], v[58:61], off offset:256
	s_waitcnt vmcnt(15)
	s_nop 1
	v_mov_b32_e32 v58, v226
	v_mov_b32_e32 v59, v227
	v_mov_b32_e32 v60, v228
	v_mov_b32_e32 v61, v229
	v_lshlrev_b32_e32 v62, 16, v58
	v_and_b32_e32 v63, 0xffff0000, v58
	v_lshlrev_b32_e32 v58, 16, v59
	v_and_b32_e32 v59, 0xffff0000, v59
	v_pk_mul_f32 v[56:57], v[56:57], v[58:59]
	v_lshlrev_b32_e32 v58, 16, v60
	v_and_b32_e32 v59, 0xffff0000, v60
	v_pk_mul_f32 v[58:59], v[50:51], v[58:59]
	v_lshlrev_b32_e32 v50, 16, v61
	v_and_b32_e32 v51, 0xffff0000, v61
	v_pk_mul_f32 v[54:55], v[54:55], v[62:63]
	v_pk_mul_f32 v[60:61], v[52:53], v[50:51]
	v_cvt_pk_bf16_f32 v50, v54, v55
	v_cvt_pk_bf16_f32 v51, v56, v57
	v_cvt_pk_bf16_f32 v52, v58, v59
	v_cvt_pk_bf16_f32 v53, v60, v61
	global_store_dwordx4 v[114:115], v[50:53], off offset:256
	s_waitcnt vmcnt(15)
	s_nop 1
	v_mov_b32_e32 v50, v230
	v_mov_b32_e32 v51, v231
	v_mov_b32_e32 v52, v232
	v_mov_b32_e32 v53, v233
	v_lshlrev_b32_e32 v54, 16, v50
	v_and_b32_e32 v55, 0xffff0000, v50
	v_lshlrev_b32_e32 v50, 16, v51
	v_and_b32_e32 v51, 0xffff0000, v51
	v_pk_mul_f32 v[48:49], v[48:49], v[50:51]
	v_lshlrev_b32_e32 v50, 16, v52
	v_and_b32_e32 v51, 0xffff0000, v52
	v_pk_mul_f32 v[50:51], v[42:43], v[50:51]
	v_lshlrev_b32_e32 v42, 16, v53
	v_and_b32_e32 v43, 0xffff0000, v53
	v_pk_mul_f32 v[46:47], v[46:47], v[54:55]
	v_pk_mul_f32 v[52:53], v[44:45], v[42:43]
	v_cvt_pk_bf16_f32 v42, v46, v47
	v_cvt_pk_bf16_f32 v43, v48, v49
	v_cvt_pk_bf16_f32 v44, v50, v51
	v_cvt_pk_bf16_f32 v45, v52, v53
	global_store_dwordx4 v[106:107], v[42:45], off offset:256
	s_waitcnt vmcnt(15)
	s_nop 1
	v_mov_b32_e32 v42, v234
	v_mov_b32_e32 v43, v235
	v_mov_b32_e32 v44, v236
	v_mov_b32_e32 v45, v237
	v_lshlrev_b32_e32 v46, 16, v42
	v_and_b32_e32 v47, 0xffff0000, v42
	v_lshlrev_b32_e32 v42, 16, v43
	v_and_b32_e32 v43, 0xffff0000, v43
	v_pk_mul_f32 v[40:41], v[40:41], v[42:43]
	v_lshlrev_b32_e32 v42, 16, v44
	v_and_b32_e32 v43, 0xffff0000, v44
	v_pk_mul_f32 v[42:43], v[34:35], v[42:43]
	v_lshlrev_b32_e32 v34, 16, v45
	v_and_b32_e32 v35, 0xffff0000, v45
	v_pk_mul_f32 v[38:39], v[38:39], v[46:47]
	v_pk_mul_f32 v[44:45], v[36:37], v[34:35]
	v_cvt_pk_bf16_f32 v34, v38, v39
	v_cvt_pk_bf16_f32 v35, v40, v41
	v_cvt_pk_bf16_f32 v36, v42, v43
	v_cvt_pk_bf16_f32 v37, v44, v45
	global_store_dwordx4 v[98:99], v[34:37], off offset:256
	s_waitcnt vmcnt(15)
	s_nop 1
	v_mov_b32_e32 v34, v238
	v_mov_b32_e32 v35, v239
	v_mov_b32_e32 v36, v240
	v_mov_b32_e32 v37, v241
	v_lshlrev_b32_e32 v38, 16, v34
	v_and_b32_e32 v39, 0xffff0000, v34
	v_lshlrev_b32_e32 v34, 16, v35
	v_and_b32_e32 v35, 0xffff0000, v35
	v_pk_mul_f32 v[32:33], v[32:33], v[34:35]
	v_lshlrev_b32_e32 v34, 16, v36
	v_and_b32_e32 v35, 0xffff0000, v36
	v_pk_mul_f32 v[34:35], v[26:27], v[34:35]
	v_lshlrev_b32_e32 v26, 16, v37
	v_and_b32_e32 v27, 0xffff0000, v37
	v_pk_mul_f32 v[30:31], v[30:31], v[38:39]
	v_pk_mul_f32 v[36:37], v[28:29], v[26:27]
	v_cvt_pk_bf16_f32 v26, v30, v31
	v_cvt_pk_bf16_f32 v27, v32, v33
	v_cvt_pk_bf16_f32 v28, v34, v35
	v_cvt_pk_bf16_f32 v29, v36, v37
	global_store_dwordx4 v[90:91], v[26:29], off offset:256
	s_waitcnt vmcnt(15)
	s_nop 1
	v_mov_b32_e32 v26, v242
	v_mov_b32_e32 v27, v243
	v_mov_b32_e32 v28, v244
	v_mov_b32_e32 v29, v245
	v_lshlrev_b32_e32 v30, 16, v26
	v_and_b32_e32 v31, 0xffff0000, v26
	v_lshlrev_b32_e32 v26, 16, v27
	v_and_b32_e32 v27, 0xffff0000, v27
	v_pk_mul_f32 v[24:25], v[24:25], v[26:27]
	v_lshlrev_b32_e32 v26, 16, v28
	v_and_b32_e32 v27, 0xffff0000, v28
	v_pk_mul_f32 v[26:27], v[18:19], v[26:27]
	v_lshlrev_b32_e32 v18, 16, v29
	v_and_b32_e32 v19, 0xffff0000, v29
	v_pk_mul_f32 v[22:23], v[22:23], v[30:31]
	v_pk_mul_f32 v[28:29], v[20:21], v[18:19]
	v_cvt_pk_bf16_f32 v18, v22, v23
	v_cvt_pk_bf16_f32 v19, v24, v25
	v_cvt_pk_bf16_f32 v20, v26, v27
	v_cvt_pk_bf16_f32 v21, v28, v29
	global_store_dwordx4 v[82:83], v[18:21], off offset:256
	s_waitcnt vmcnt(15)
	s_nop 1
	v_mov_b32_e32 v18, v190
	v_mov_b32_e32 v19, v191
	v_mov_b32_e32 v20, v192
	v_mov_b32_e32 v21, v193
	v_lshlrev_b32_e32 v22, 16, v18
	v_and_b32_e32 v23, 0xffff0000, v18
	v_lshlrev_b32_e32 v18, 16, v19
	v_and_b32_e32 v19, 0xffff0000, v19
	v_pk_mul_f32 v[16:17], v[16:17], v[18:19]
	v_lshlrev_b32_e32 v18, 16, v20
	v_and_b32_e32 v19, 0xffff0000, v20
	v_pk_mul_f32 v[18:19], v[10:11], v[18:19]
	v_lshlrev_b32_e32 v10, 16, v21
	v_and_b32_e32 v11, 0xffff0000, v21
	v_pk_mul_f32 v[14:15], v[14:15], v[22:23]
	v_pk_mul_f32 v[20:21], v[12:13], v[10:11]
	v_cvt_pk_bf16_f32 v10, v14, v15
	v_cvt_pk_bf16_f32 v11, v16, v17
	v_cvt_pk_bf16_f32 v12, v18, v19
	v_cvt_pk_bf16_f32 v13, v20, v21
	global_store_dwordx4 v[74:75], v[10:13], off offset:256
	s_waitcnt vmcnt(14)
	s_nop 1
	v_mov_b32_e32 v10, v194
	v_mov_b32_e32 v11, v195
	v_mov_b32_e32 v12, v196
	v_mov_b32_e32 v13, v197
	v_lshlrev_b32_e32 v14, 16, v10
	v_and_b32_e32 v15, 0xffff0000, v10
	v_lshlrev_b32_e32 v10, 16, v11
	v_and_b32_e32 v11, 0xffff0000, v11
	v_pk_mul_f32 v[8:9], v[8:9], v[10:11]
	v_lshlrev_b32_e32 v10, 16, v12
	v_and_b32_e32 v11, 0xffff0000, v12
	v_pk_mul_f32 v[10:11], v[0:1], v[10:11]
	v_lshlrev_b32_e32 v0, 16, v13
	v_and_b32_e32 v1, 0xffff0000, v13
	v_pk_mul_f32 v[6:7], v[6:7], v[14:15]
	v_pk_mul_f32 v[12:13], v[2:3], v[0:1]
	v_cvt_pk_bf16_f32 v0, v6, v7
	v_cvt_pk_bf16_f32 v1, v8, v9
	v_cvt_pk_bf16_f32 v2, v10, v11
	v_cvt_pk_bf16_f32 v3, v12, v13
	global_store_dwordx4 v[66:67], v[0:3], off offset:256
	s_cbranch_vccnz .LBB0_195
	s_andn2_b64 vcc, exec, s[44:45]
	s_cbranch_vccnz .LBB0_194
	s_barrier
	s_branch .LBB0_194

.LBB0_231:
	v_lshl_add_u32 v146, s52, 8, v148
	v_lshl_or_b32 v140, s51, 8, v150
	v_ashrrev_i32_e32 v141, 31, v140
	v_ashrrev_i32_e32 v147, 31, v146
	v_readlane_b32 s2, v252, 19
	v_readlane_b32 s0, v254, 1
	v_lshlrev_b64 v[142:143], 13, v[146:147]
	v_readlane_b32 s3, v252, 20
	v_lshlrev_b64 v[144:145], 1, v[140:141]
	v_lshlrev_b64 v[140:141], 12, v[146:147]
	v_readlane_b32 s1, v254, 2
	v_lshl_add_u64 v[142:143], s[2:3], 0, v[142:143]
	v_lshl_add_u64 v[142:143], v[142:143], 0, v[144:145]
	v_lshl_add_u64 v[140:141], s[0:1], 0, v[140:141]
	v_lshl_add_u64 v[140:141], v[140:141], 0, v[144:145]
	global_load_dwordx4 v[172:175], v[142:143], off
	global_load_dwordx4 v[190:193], v[140:141], off
	v_lshl_add_u32 v162, v146, 13, v144
	v_lshl_add_u32 v163, v146, 12, v144
	v_add_u32_e32 v166, 0x20000, v162
	v_add_u32_e32 v167, 0x10000, v163
	global_load_dwordx4 v[194:197], v166, s[2:3]
	global_load_dwordx4 v[198:201], v167, s[0:1]
	v_add_u32_e32 v166, 0x40000, v162
	v_add_u32_e32 v167, 0x20000, v163
	global_load_dwordx4 v[202:205], v166, s[2:3]
	global_load_dwordx4 v[206:209], v167, s[0:1]
	v_add_u32_e32 v166, 0x60000, v162
	v_add_u32_e32 v167, 0x30000, v163
	global_load_dwordx4 v[210:213], v166, s[2:3]
	global_load_dwordx4 v[214:217], v167, s[0:1]
	v_add_u32_e32 v166, 0x100000, v162
	v_add_u32_e32 v167, 0x80000, v163
	global_load_dwordx4 v[218:221], v166, s[2:3]
	global_load_dwordx4 v[222:225], v167, s[0:1]
	v_add_u32_e32 v166, 0x120000, v162
	v_add_u32_e32 v167, 0x90000, v163
	global_load_dwordx4 v[226:229], v166, s[2:3]
	global_load_dwordx4 v[230:233], v167, s[0:1]
	v_add_u32_e32 v166, 0x140000, v162
	v_add_u32_e32 v167, 0xa0000, v163
	global_load_dwordx4 v[234:237], v166, s[2:3]
	global_load_dwordx4 v[238:241], v167, s[0:1]
	s_and_b64 vcc, exec, s[38:39]
	s_waitcnt vmcnt(12)
	v_lshlrev_b32_e32 v162, 16, v172
	v_and_b32_e32 v163, 0xffff0000, v172
	v_lshlrev_b32_e32 v166, 16, v190
	v_and_b32_e32 v167, 0xffff0000, v190
	v_pk_fma_f32 v[126:127], v[126:127], v[162:163], v[166:167]
	v_lshlrev_b32_e32 v162, 16, v173
	v_and_b32_e32 v163, 0xffff0000, v173
	v_lshlrev_b32_e32 v166, 16, v191
	v_and_b32_e32 v167, 0xffff0000, v191
	v_pk_fma_f32 v[128:129], v[128:129], v[162:163], v[166:167]
	v_lshlrev_b32_e32 v162, 16, v174
	v_and_b32_e32 v163, 0xffff0000, v174
	v_lshlrev_b32_e32 v166, 16, v192
	v_and_b32_e32 v167, 0xffff0000, v192
	v_pk_fma_f32 v[162:163], v[122:123], v[162:163], v[166:167]
	v_lshlrev_b32_e32 v122, 16, v175
	v_and_b32_e32 v123, 0xffff0000, v175
	v_lshlrev_b32_e32 v166, 16, v193
	v_and_b32_e32 v167, 0xffff0000, v193
	v_pk_fma_f32 v[166:167], v[124:125], v[122:123], v[166:167]
	v_cvt_pk_bf16_f32 v122, v126, v127
	v_cvt_pk_bf16_f32 v123, v128, v129
	v_cvt_pk_bf16_f32 v124, v162, v163
	v_cvt_pk_bf16_f32 v125, v166, v167
	global_store_dwordx4 v[140:141], v[122:125], off
	s_nop 1
	v_or_b32_e32 v124, 16, v146
	v_ashrrev_i32_e32 v125, 31, v124
	v_lshlrev_b64 v[122:123], 13, v[124:125]
	v_lshlrev_b64 v[124:125], 12, v[124:125]
	v_lshl_add_u64 v[122:123], s[2:3], 0, v[122:123]
	v_lshl_add_u64 v[124:125], s[0:1], 0, v[124:125]
	v_lshl_add_u64 v[122:123], v[122:123], 0, v[144:145]
	v_lshl_add_u64 v[124:125], v[124:125], 0, v[144:145]
	s_waitcnt vmcnt(11)
	s_nop 1
	v_mov_b32_e32 v126, v194
	v_mov_b32_e32 v127, v195
	v_mov_b32_e32 v128, v196
	v_mov_b32_e32 v129, v197
	v_mov_b32_e32 v172, v198
	v_mov_b32_e32 v173, v199
	v_mov_b32_e32 v174, v200
	v_mov_b32_e32 v175, v201
	v_lshl_add_u32 v166, v146, 13, v144
	v_lshl_add_u32 v167, v146, 12, v144
	v_add_u32_e32 v166, 0x160000, v166
	v_add_u32_e32 v167, 0xb0000, v167
	global_load_dwordx4 v[194:197], v166, s[2:3]
	global_load_dwordx4 v[198:201], v167, s[0:1]
	v_lshlrev_b32_e32 v162, 16, v126
	v_and_b32_e32 v163, 0xffff0000, v126
	v_lshlrev_b32_e32 v166, 16, v172
	v_and_b32_e32 v167, 0xffff0000, v172
	v_pk_fma_f32 v[118:119], v[118:119], v[162:163], v[166:167]
	v_lshlrev_b32_e32 v126, 16, v127
	v_and_b32_e32 v127, 0xffff0000, v127
	v_lshlrev_b32_e32 v162, 16, v173
	v_and_b32_e32 v163, 0xffff0000, v173
	v_pk_fma_f32 v[120:121], v[120:121], v[126:127], v[162:163]
	v_lshlrev_b32_e32 v126, 16, v128
	v_and_b32_e32 v127, 0xffff0000, v128
	v_lshlrev_b32_e32 v162, 16, v174
	v_and_b32_e32 v163, 0xffff0000, v174
	v_pk_fma_f32 v[126:127], v[114:115], v[126:127], v[162:163]
	v_lshlrev_b32_e32 v114, 16, v129
	v_and_b32_e32 v115, 0xffff0000, v129
	v_lshlrev_b32_e32 v128, 16, v175
	v_and_b32_e32 v129, 0xffff0000, v175
	v_pk_fma_f32 v[128:129], v[116:117], v[114:115], v[128:129]
	v_cvt_pk_bf16_f32 v114, v118, v119
	v_cvt_pk_bf16_f32 v115, v120, v121
	v_cvt_pk_bf16_f32 v116, v126, v127
	v_cvt_pk_bf16_f32 v117, v128, v129
	global_store_dwordx4 v[124:125], v[114:117], off
	s_nop 1
	v_or_b32_e32 v116, 32, v146
	v_ashrrev_i32_e32 v117, 31, v116
	v_lshlrev_b64 v[114:115], 13, v[116:117]
	v_lshlrev_b64 v[116:117], 12, v[116:117]
	v_lshl_add_u64 v[114:115], s[2:3], 0, v[114:115]
	v_lshl_add_u64 v[116:117], s[0:1], 0, v[116:117]
	v_lshl_add_u64 v[114:115], v[114:115], 0, v[144:145]
	v_lshl_add_u64 v[116:117], v[116:117], 0, v[144:145]
	s_waitcnt vmcnt(12)
	s_nop 1
	v_mov_b32_e32 v118, v202
	v_mov_b32_e32 v119, v203
	v_mov_b32_e32 v120, v204
	v_mov_b32_e32 v121, v205
	v_mov_b32_e32 v126, v206
	v_mov_b32_e32 v127, v207
	v_mov_b32_e32 v128, v208
	v_mov_b32_e32 v129, v209
	v_lshl_add_u32 v166, v146, 13, v144
	v_lshl_add_u32 v167, v146, 12, v144
	global_load_dwordx4 v[202:205], v166, s[2:3] offset:256
	global_load_dwordx4 v[206:209], v167, s[0:1] offset:256
	v_lshlrev_b32_e32 v162, 16, v118
	v_and_b32_e32 v163, 0xffff0000, v118
	v_lshlrev_b32_e32 v166, 16, v126
	v_and_b32_e32 v167, 0xffff0000, v126
	v_lshlrev_b32_e32 v118, 16, v119
	v_and_b32_e32 v119, 0xffff0000, v119
	v_lshlrev_b32_e32 v126, 16, v127
	v_and_b32_e32 v127, 0xffff0000, v127
	v_pk_fma_f32 v[112:113], v[112:113], v[118:119], v[126:127]
	v_lshlrev_b32_e32 v118, 16, v120
	v_and_b32_e32 v119, 0xffff0000, v120
	v_lshlrev_b32_e32 v126, 16, v128
	v_and_b32_e32 v127, 0xffff0000, v128
	v_pk_fma_f32 v[118:119], v[106:107], v[118:119], v[126:127]
	v_lshlrev_b32_e32 v106, 16, v121
	v_and_b32_e32 v107, 0xffff0000, v121
	v_lshlrev_b32_e32 v120, 16, v129
	v_and_b32_e32 v121, 0xffff0000, v129
	v_pk_fma_f32 v[110:111], v[110:111], v[162:163], v[166:167]
	v_pk_fma_f32 v[120:121], v[108:109], v[106:107], v[120:121]
	v_cvt_pk_bf16_f32 v106, v110, v111
	v_cvt_pk_bf16_f32 v107, v112, v113
	v_cvt_pk_bf16_f32 v108, v118, v119
	v_cvt_pk_bf16_f32 v109, v120, v121
	global_store_dwordx4 v[116:117], v[106:109], off
	s_nop 1
	v_or_b32_e32 v108, 48, v146
	v_ashrrev_i32_e32 v109, 31, v108
	v_lshlrev_b64 v[106:107], 13, v[108:109]
	v_lshlrev_b64 v[108:109], 12, v[108:109]
	v_lshl_add_u64 v[106:107], s[2:3], 0, v[106:107]
	v_lshl_add_u64 v[108:109], s[0:1], 0, v[108:109]
	v_lshl_add_u64 v[106:107], v[106:107], 0, v[144:145]
	v_lshl_add_u64 v[108:109], v[108:109], 0, v[144:145]
	s_waitcnt vmcnt(13)
	s_nop 1
	v_mov_b32_e32 v110, v210
	v_mov_b32_e32 v111, v211
	v_mov_b32_e32 v112, v212
	v_mov_b32_e32 v113, v213
	v_mov_b32_e32 v118, v214
	v_mov_b32_e32 v119, v215
	v_mov_b32_e32 v120, v216
	v_mov_b32_e32 v121, v217
	v_lshl_add_u32 v166, v146, 13, v144
	v_lshl_add_u32 v167, v146, 12, v144
	v_add_u32_e32 v166, 0x20000, v166
	v_add_u32_e32 v167, 0x10000, v167
	global_load_dwordx4 v[210:213], v166, s[2:3] offset:256
	global_load_dwordx4 v[214:217], v167, s[0:1] offset:256
	v_lshlrev_b32_e32 v126, 16, v110
	v_and_b32_e32 v127, 0xffff0000, v110
	v_lshlrev_b32_e32 v128, 16, v118
	v_and_b32_e32 v129, 0xffff0000, v118
	v_lshlrev_b32_e32 v110, 16, v111
	v_and_b32_e32 v111, 0xffff0000, v111
	v_lshlrev_b32_e32 v118, 16, v119
	v_and_b32_e32 v119, 0xffff0000, v119
	v_pk_fma_f32 v[104:105], v[104:105], v[110:111], v[118:119]
	v_lshlrev_b32_e32 v110, 16, v112
	v_and_b32_e32 v111, 0xffff0000, v112
	v_lshlrev_b32_e32 v118, 16, v120
	v_and_b32_e32 v119, 0xffff0000, v120
	v_pk_fma_f32 v[110:111], v[98:99], v[110:111], v[118:119]
	v_lshlrev_b32_e32 v98, 16, v113
	v_and_b32_e32 v99, 0xffff0000, v113
	v_lshlrev_b32_e32 v112, 16, v121
	v_and_b32_e32 v113, 0xffff0000, v121
	v_pk_fma_f32 v[102:103], v[102:103], v[126:127], v[128:129]
	v_pk_fma_f32 v[112:113], v[100:101], v[98:99], v[112:113]
	v_cvt_pk_bf16_f32 v98, v102, v103
	v_cvt_pk_bf16_f32 v99, v104, v105
	v_cvt_pk_bf16_f32 v100, v110, v111
	v_cvt_pk_bf16_f32 v101, v112, v113
	global_store_dwordx4 v[108:109], v[98:101], off
	s_nop 1
	v_add_u32_e32 v100, 0x80, v146
	v_ashrrev_i32_e32 v101, 31, v100
	v_lshlrev_b64 v[98:99], 13, v[100:101]
	v_lshlrev_b64 v[100:101], 12, v[100:101]
	v_lshl_add_u64 v[98:99], s[2:3], 0, v[98:99]
	v_lshl_add_u64 v[100:101], s[0:1], 0, v[100:101]
	v_lshl_add_u64 v[98:99], v[98:99], 0, v[144:145]
	v_lshl_add_u64 v[100:101], v[100:101], 0, v[144:145]
	s_waitcnt vmcnt(14)
	s_nop 1
	v_mov_b32_e32 v102, v218
	v_mov_b32_e32 v103, v219
	v_mov_b32_e32 v104, v220
	v_mov_b32_e32 v105, v221
	v_mov_b32_e32 v110, v222
	v_mov_b32_e32 v111, v223
	v_mov_b32_e32 v112, v224
	v_mov_b32_e32 v113, v225
	v_lshl_add_u32 v166, v146, 13, v144
	v_lshl_add_u32 v167, v146, 12, v144
	v_add_u32_e32 v166, 0x40000, v166
	v_add_u32_e32 v167, 0x20000, v167
	global_load_dwordx4 v[218:221], v166, s[2:3] offset:256
	global_load_dwordx4 v[222:225], v167, s[0:1] offset:256
	v_lshlrev_b32_e32 v118, 16, v102
	v_and_b32_e32 v119, 0xffff0000, v102
	v_lshlrev_b32_e32 v120, 16, v110
	v_and_b32_e32 v121, 0xffff0000, v110
	v_lshlrev_b32_e32 v102, 16, v103
	v_and_b32_e32 v103, 0xffff0000, v103
	v_lshlrev_b32_e32 v110, 16, v111
	v_and_b32_e32 v111, 0xffff0000, v111
	v_pk_fma_f32 v[96:97], v[96:97], v[102:103], v[110:111]
	v_lshlrev_b32_e32 v102, 16, v104
	v_and_b32_e32 v103, 0xffff0000, v104
	v_lshlrev_b32_e32 v110, 16, v112
	v_and_b32_e32 v111, 0xffff0000, v112
	v_pk_fma_f32 v[102:103], v[90:91], v[102:103], v[110:111]
	v_lshlrev_b32_e32 v90, 16, v105
	v_and_b32_e32 v91, 0xffff0000, v105
	v_lshlrev_b32_e32 v104, 16, v113
	v_and_b32_e32 v105, 0xffff0000, v113
	v_pk_fma_f32 v[94:95], v[94:95], v[118:119], v[120:121]
	v_pk_fma_f32 v[104:105], v[92:93], v[90:91], v[104:105]
	v_cvt_pk_bf16_f32 v90, v94, v95
	v_cvt_pk_bf16_f32 v91, v96, v97
	v_cvt_pk_bf16_f32 v92, v102, v103
	v_cvt_pk_bf16_f32 v93, v104, v105
	global_store_dwordx4 v[100:101], v[90:93], off
	s_nop 1
	v_add_u32_e32 v92, 0x90, v146
	v_ashrrev_i32_e32 v93, 31, v92
	v_lshlrev_b64 v[90:91], 13, v[92:93]
	v_lshlrev_b64 v[92:93], 12, v[92:93]
	v_lshl_add_u64 v[90:91], s[2:3], 0, v[90:91]
	v_lshl_add_u64 v[92:93], s[0:1], 0, v[92:93]
	v_lshl_add_u64 v[90:91], v[90:91], 0, v[144:145]
	v_lshl_add_u64 v[92:93], v[92:93], 0, v[144:145]
	s_waitcnt vmcnt(15)
	s_nop 1
	v_mov_b32_e32 v94, v226
	v_mov_b32_e32 v95, v227
	v_mov_b32_e32 v96, v228
	v_mov_b32_e32 v97, v229
	v_mov_b32_e32 v102, v230
	v_mov_b32_e32 v103, v231
	v_mov_b32_e32 v104, v232
	v_mov_b32_e32 v105, v233
	v_lshl_add_u32 v166, v146, 13, v144
	v_lshl_add_u32 v167, v146, 12, v144
	v_add_u32_e32 v166, 0x60000, v166
	v_add_u32_e32 v167, 0x30000, v167
	global_load_dwordx4 v[226:229], v166, s[2:3] offset:256
	global_load_dwordx4 v[230:233], v167, s[0:1] offset:256
	v_lshlrev_b32_e32 v110, 16, v94
	v_and_b32_e32 v111, 0xffff0000, v94
	v_lshlrev_b32_e32 v112, 16, v102
	v_and_b32_e32 v113, 0xffff0000, v102
	v_lshlrev_b32_e32 v94, 16, v95
	v_and_b32_e32 v95, 0xffff0000, v95
	v_lshlrev_b32_e32 v102, 16, v103
	v_and_b32_e32 v103, 0xffff0000, v103
	v_pk_fma_f32 v[88:89], v[88:89], v[94:95], v[102:103]
	v_lshlrev_b32_e32 v94, 16, v96
	v_and_b32_e32 v95, 0xffff0000, v96
	v_lshlrev_b32_e32 v102, 16, v104
	v_and_b32_e32 v103, 0xffff0000, v104
	v_pk_fma_f32 v[94:95], v[82:83], v[94:95], v[102:103]
	v_lshlrev_b32_e32 v82, 16, v97
	v_and_b32_e32 v83, 0xffff0000, v97
	v_lshlrev_b32_e32 v96, 16, v105
	v_and_b32_e32 v97, 0xffff0000, v105
	v_pk_fma_f32 v[86:87], v[86:87], v[110:111], v[112:113]
	v_pk_fma_f32 v[96:97], v[84:85], v[82:83], v[96:97]
	v_cvt_pk_bf16_f32 v82, v86, v87
	v_cvt_pk_bf16_f32 v83, v88, v89
	v_cvt_pk_bf16_f32 v84, v94, v95
	v_cvt_pk_bf16_f32 v85, v96, v97
	global_store_dwordx4 v[92:93], v[82:85], off
	s_nop 1
	v_add_u32_e32 v84, 0xa0, v146
	v_ashrrev_i32_e32 v85, 31, v84
	v_lshlrev_b64 v[82:83], 13, v[84:85]
	v_lshlrev_b64 v[84:85], 12, v[84:85]
	v_lshl_add_u64 v[82:83], s[2:3], 0, v[82:83]
	v_lshl_add_u64 v[84:85], s[0:1], 0, v[84:85]
	v_lshl_add_u64 v[82:83], v[82:83], 0, v[144:145]
	v_lshl_add_u64 v[84:85], v[84:85], 0, v[144:145]
	s_waitcnt vmcnt(16)
	s_nop 1
	v_mov_b32_e32 v86, v234
	v_mov_b32_e32 v87, v235
	v_mov_b32_e32 v88, v236
	v_mov_b32_e32 v89, v237
	v_mov_b32_e32 v94, v238
	v_mov_b32_e32 v95, v239
	v_mov_b32_e32 v96, v240
	v_mov_b32_e32 v97, v241
	v_lshl_add_u32 v166, v146, 13, v144
	v_lshl_add_u32 v167, v146, 12, v144
	v_add_u32_e32 v166, 0x100000, v166
	v_add_u32_e32 v167, 0x80000, v167
	global_load_dwordx4 v[234:237], v166, s[2:3] offset:256
	global_load_dwordx4 v[238:241], v167, s[0:1] offset:256
	v_lshlrev_b32_e32 v102, 16, v86
	v_and_b32_e32 v103, 0xffff0000, v86
	v_lshlrev_b32_e32 v104, 16, v94
	v_and_b32_e32 v105, 0xffff0000, v94
	v_lshlrev_b32_e32 v86, 16, v87
	v_and_b32_e32 v87, 0xffff0000, v87
	v_lshlrev_b32_e32 v94, 16, v95
	v_and_b32_e32 v95, 0xffff0000, v95
	v_pk_fma_f32 v[80:81], v[80:81], v[86:87], v[94:95]
	v_lshlrev_b32_e32 v86, 16, v88
	v_and_b32_e32 v87, 0xffff0000, v88
	v_lshlrev_b32_e32 v94, 16, v96
	v_and_b32_e32 v95, 0xffff0000, v96
	v_pk_fma_f32 v[86:87], v[74:75], v[86:87], v[94:95]
	v_lshlrev_b32_e32 v74, 16, v89
	v_and_b32_e32 v75, 0xffff0000, v89
	v_lshlrev_b32_e32 v88, 16, v97
	v_and_b32_e32 v89, 0xffff0000, v97
	v_pk_fma_f32 v[78:79], v[78:79], v[102:103], v[104:105]
	v_pk_fma_f32 v[88:89], v[76:77], v[74:75], v[88:89]
	v_cvt_pk_bf16_f32 v74, v78, v79
	v_cvt_pk_bf16_f32 v75, v80, v81
	v_cvt_pk_bf16_f32 v76, v86, v87
	v_cvt_pk_bf16_f32 v77, v88, v89
	global_store_dwordx4 v[84:85], v[74:77], off
	s_nop 1
	v_add_u32_e32 v76, 0xb0, v146
	v_ashrrev_i32_e32 v77, 31, v76
	v_lshlrev_b64 v[74:75], 13, v[76:77]
	v_lshlrev_b64 v[76:77], 12, v[76:77]
	v_lshl_add_u64 v[74:75], s[2:3], 0, v[74:75]
	v_lshl_add_u64 v[76:77], s[0:1], 0, v[76:77]
	v_lshl_add_u64 v[74:75], v[74:75], 0, v[144:145]
	v_lshl_add_u64 v[76:77], v[76:77], 0, v[144:145]
	s_waitcnt vmcnt(16)
	s_nop 1
	v_mov_b32_e32 v78, v194
	v_mov_b32_e32 v79, v195
	v_mov_b32_e32 v80, v196
	v_mov_b32_e32 v81, v197
	v_mov_b32_e32 v86, v198
	v_mov_b32_e32 v87, v199
	v_mov_b32_e32 v88, v200
	v_mov_b32_e32 v89, v201
	v_lshl_add_u32 v166, v146, 13, v144
	v_lshl_add_u32 v167, v146, 12, v144
	v_add_u32_e32 v166, 0x120000, v166
	v_add_u32_e32 v167, 0x90000, v167
	global_load_dwordx4 v[194:197], v166, s[2:3] offset:256
	global_load_dwordx4 v[198:201], v167, s[0:1] offset:256
	v_lshlrev_b32_e32 v94, 16, v78
	v_and_b32_e32 v95, 0xffff0000, v78
	v_lshlrev_b32_e32 v96, 16, v86
	v_and_b32_e32 v97, 0xffff0000, v86
	v_lshlrev_b32_e32 v78, 16, v79
	v_and_b32_e32 v79, 0xffff0000, v79
	v_lshlrev_b32_e32 v86, 16, v87
	v_and_b32_e32 v87, 0xffff0000, v87
	v_pk_fma_f32 v[72:73], v[72:73], v[78:79], v[86:87]
	v_lshlrev_b32_e32 v78, 16, v80
	v_and_b32_e32 v79, 0xffff0000, v80
	v_lshlrev_b32_e32 v86, 16, v88
	v_and_b32_e32 v87, 0xffff0000, v88
	v_pk_fma_f32 v[78:79], v[62:63], v[78:79], v[86:87]
	v_lshlrev_b32_e32 v62, 16, v81
	v_and_b32_e32 v63, 0xffff0000, v81
	v_lshlrev_b32_e32 v80, 16, v89
	v_and_b32_e32 v81, 0xffff0000, v89
	v_pk_fma_f32 v[70:71], v[70:71], v[94:95], v[96:97]
	v_pk_fma_f32 v[80:81], v[64:65], v[62:63], v[80:81]
	v_cvt_pk_bf16_f32 v62, v70, v71
	v_cvt_pk_bf16_f32 v63, v72, v73
	v_cvt_pk_bf16_f32 v64, v78, v79
	v_cvt_pk_bf16_f32 v65, v80, v81
	global_store_dwordx4 v[76:77], v[62:65], off
	s_waitcnt vmcnt(16)
	s_nop 1
	v_mov_b32_e32 v62, v202
	v_mov_b32_e32 v63, v203
	v_mov_b32_e32 v64, v204
	v_mov_b32_e32 v65, v205
	v_mov_b32_e32 v70, v206
	v_mov_b32_e32 v71, v207
	v_mov_b32_e32 v72, v208
	v_mov_b32_e32 v73, v209
	v_lshl_add_u32 v166, v146, 13, v144
	v_lshl_add_u32 v167, v146, 12, v144
	v_add_u32_e32 v166, 0x140000, v166
	v_add_u32_e32 v167, 0xa0000, v167
	global_load_dwordx4 v[202:205], v166, s[2:3] offset:256
	global_load_dwordx4 v[206:209], v167, s[0:1] offset:256
	v_lshlrev_b32_e32 v78, 16, v62
	v_and_b32_e32 v79, 0xffff0000, v62
	v_lshlrev_b32_e32 v80, 16, v70
	v_and_b32_e32 v81, 0xffff0000, v70
	v_lshlrev_b32_e32 v62, 16, v63
	v_and_b32_e32 v63, 0xffff0000, v63
	v_lshlrev_b32_e32 v70, 16, v71
	v_and_b32_e32 v71, 0xffff0000, v71
	v_pk_fma_f32 v[62:63], v[68:69], v[62:63], v[70:71]
	v_lshlrev_b32_e32 v68, 16, v64
	v_and_b32_e32 v69, 0xffff0000, v64
	v_lshlrev_b32_e32 v70, 16, v72
	v_and_b32_e32 v71, 0xffff0000, v72
	v_pk_fma_f32 v[68:69], v[58:59], v[68:69], v[70:71]
	v_lshlrev_b32_e32 v58, 16, v65
	v_and_b32_e32 v59, 0xffff0000, v65
	v_lshlrev_b32_e32 v64, 16, v73
	v_and_b32_e32 v65, 0xffff0000, v73
	v_pk_fma_f32 v[66:67], v[66:67], v[78:79], v[80:81]
	v_pk_fma_f32 v[64:65], v[60:61], v[58:59], v[64:65]
	v_cvt_pk_bf16_f32 v58, v66, v67
	v_cvt_pk_bf16_f32 v59, v62, v63
	v_cvt_pk_bf16_f32 v60, v68, v69
	v_cvt_pk_bf16_f32 v61, v64, v65
	global_store_dwordx4 v[140:141], v[58:61], off offset:256
	s_waitcnt vmcnt(16)
	s_nop 1
	v_mov_b32_e32 v58, v210
	v_mov_b32_e32 v59, v211
	v_mov_b32_e32 v60, v212
	v_mov_b32_e32 v61, v213
	v_mov_b32_e32 v62, v214
	v_mov_b32_e32 v63, v215
	v_mov_b32_e32 v64, v216
	v_mov_b32_e32 v65, v217
	v_lshl_add_u32 v166, v146, 13, v144
	v_lshl_add_u32 v167, v146, 12, v144
	v_add_u32_e32 v166, 0x160000, v166
	v_add_u32_e32 v167, 0xb0000, v167
	global_load_dwordx4 v[210:213], v166, s[2:3] offset:256
	global_load_dwordx4 v[214:217], v167, s[0:1] offset:256
	v_lshlrev_b32_e32 v66, 16, v58
	v_and_b32_e32 v67, 0xffff0000, v58
	v_lshlrev_b32_e32 v68, 16, v62
	v_and_b32_e32 v69, 0xffff0000, v62
	v_lshlrev_b32_e32 v58, 16, v59
	v_and_b32_e32 v59, 0xffff0000, v59
	v_lshlrev_b32_e32 v62, 16, v63
	v_and_b32_e32 v63, 0xffff0000, v63
	v_pk_fma_f32 v[56:57], v[56:57], v[58:59], v[62:63]
	v_lshlrev_b32_e32 v58, 16, v60
	v_and_b32_e32 v59, 0xffff0000, v60
	v_lshlrev_b32_e32 v62, 16, v64
	v_and_b32_e32 v63, 0xffff0000, v64
	v_pk_fma_f32 v[58:59], v[50:51], v[58:59], v[62:63]
	v_lshlrev_b32_e32 v50, 16, v61
	v_and_b32_e32 v51, 0xffff0000, v61
	v_lshlrev_b32_e32 v60, 16, v65
	v_and_b32_e32 v61, 0xffff0000, v65
	v_pk_fma_f32 v[54:55], v[54:55], v[66:67], v[68:69]
	v_pk_fma_f32 v[60:61], v[52:53], v[50:51], v[60:61]
	v_cvt_pk_bf16_f32 v50, v54, v55
	v_cvt_pk_bf16_f32 v51, v56, v57
	v_cvt_pk_bf16_f32 v52, v58, v59
	v_cvt_pk_bf16_f32 v53, v60, v61
	global_store_dwordx4 v[124:125], v[50:53], off offset:256
	s_waitcnt vmcnt(16)
	s_nop 1
	v_mov_b32_e32 v50, v218
	v_mov_b32_e32 v51, v219
	v_mov_b32_e32 v52, v220
	v_mov_b32_e32 v53, v221
	v_mov_b32_e32 v54, v222
	v_mov_b32_e32 v55, v223
	v_mov_b32_e32 v56, v224
	v_mov_b32_e32 v57, v225
	v_lshlrev_b32_e32 v58, 16, v50
	v_and_b32_e32 v59, 0xffff0000, v50
	v_lshlrev_b32_e32 v60, 16, v54
	v_and_b32_e32 v61, 0xffff0000, v54
	v_lshlrev_b32_e32 v50, 16, v51
	v_and_b32_e32 v51, 0xffff0000, v51
	v_lshlrev_b32_e32 v54, 16, v55
	v_and_b32_e32 v55, 0xffff0000, v55
	v_pk_fma_f32 v[48:49], v[48:49], v[50:51], v[54:55]
	v_lshlrev_b32_e32 v50, 16, v52
	v_and_b32_e32 v51, 0xffff0000, v52
	v_lshlrev_b32_e32 v54, 16, v56
	v_and_b32_e32 v55, 0xffff0000, v56
	v_pk_fma_f32 v[50:51], v[42:43], v[50:51], v[54:55]
	v_lshlrev_b32_e32 v42, 16, v53
	v_and_b32_e32 v43, 0xffff0000, v53
	v_lshlrev_b32_e32 v52, 16, v57
	v_and_b32_e32 v53, 0xffff0000, v57
	v_pk_fma_f32 v[46:47], v[46:47], v[58:59], v[60:61]
	v_pk_fma_f32 v[52:53], v[44:45], v[42:43], v[52:53]
	v_cvt_pk_bf16_f32 v42, v46, v47
	v_cvt_pk_bf16_f32 v43, v48, v49
	v_cvt_pk_bf16_f32 v44, v50, v51
	v_cvt_pk_bf16_f32 v45, v52, v53
	global_store_dwordx4 v[116:117], v[42:45], off offset:256
	s_waitcnt vmcnt(14)
	s_nop 1
	v_mov_b32_e32 v42, v226
	v_mov_b32_e32 v43, v227
	v_mov_b32_e32 v44, v228
	v_mov_b32_e32 v45, v229
	v_mov_b32_e32 v46, v230
	v_mov_b32_e32 v47, v231
	v_mov_b32_e32 v48, v232
	v_mov_b32_e32 v49, v233
	v_lshlrev_b32_e32 v50, 16, v42
	v_and_b32_e32 v51, 0xffff0000, v42
	v_lshlrev_b32_e32 v52, 16, v46
	v_and_b32_e32 v53, 0xffff0000, v46
	v_lshlrev_b32_e32 v42, 16, v43
	v_and_b32_e32 v43, 0xffff0000, v43
	v_lshlrev_b32_e32 v46, 16, v47
	v_and_b32_e32 v47, 0xffff0000, v47
	v_pk_fma_f32 v[40:41], v[40:41], v[42:43], v[46:47]
	v_lshlrev_b32_e32 v42, 16, v44
	v_and_b32_e32 v43, 0xffff0000, v44
	v_lshlrev_b32_e32 v46, 16, v48
	v_and_b32_e32 v47, 0xffff0000, v48
	v_pk_fma_f32 v[42:43], v[34:35], v[42:43], v[46:47]
	v_lshlrev_b32_e32 v34, 16, v45
	v_and_b32_e32 v35, 0xffff0000, v45
	v_lshlrev_b32_e32 v44, 16, v49
	v_and_b32_e32 v45, 0xffff0000, v49
	v_pk_fma_f32 v[38:39], v[38:39], v[50:51], v[52:53]
	v_pk_fma_f32 v[44:45], v[36:37], v[34:35], v[44:45]
	v_cvt_pk_bf16_f32 v34, v38, v39
	v_cvt_pk_bf16_f32 v35, v40, v41
	v_cvt_pk_bf16_f32 v36, v42, v43
	v_cvt_pk_bf16_f32 v37, v44, v45
	global_store_dwordx4 v[108:109], v[34:37], off offset:256
	s_waitcnt vmcnt(12)
	s_nop 1
	v_mov_b32_e32 v34, v234
	v_mov_b32_e32 v35, v235
	v_mov_b32_e32 v36, v236
	v_mov_b32_e32 v37, v237
	v_mov_b32_e32 v38, v238
	v_mov_b32_e32 v39, v239
	v_mov_b32_e32 v40, v240
	v_mov_b32_e32 v41, v241
	v_lshlrev_b32_e32 v42, 16, v34
	v_and_b32_e32 v43, 0xffff0000, v34
	v_lshlrev_b32_e32 v44, 16, v38
	v_and_b32_e32 v45, 0xffff0000, v38
	v_lshlrev_b32_e32 v34, 16, v35
	v_and_b32_e32 v35, 0xffff0000, v35
	v_lshlrev_b32_e32 v38, 16, v39
	v_and_b32_e32 v39, 0xffff0000, v39
	v_pk_fma_f32 v[32:33], v[32:33], v[34:35], v[38:39]
	v_lshlrev_b32_e32 v34, 16, v36
	v_and_b32_e32 v35, 0xffff0000, v36
	v_lshlrev_b32_e32 v38, 16, v40
	v_and_b32_e32 v39, 0xffff0000, v40
	v_pk_fma_f32 v[34:35], v[26:27], v[34:35], v[38:39]
	v_lshlrev_b32_e32 v26, 16, v37
	v_and_b32_e32 v27, 0xffff0000, v37
	v_lshlrev_b32_e32 v36, 16, v41
	v_and_b32_e32 v37, 0xffff0000, v41
	v_pk_fma_f32 v[30:31], v[30:31], v[42:43], v[44:45]
	v_pk_fma_f32 v[36:37], v[28:29], v[26:27], v[36:37]
	v_cvt_pk_bf16_f32 v26, v30, v31
	v_cvt_pk_bf16_f32 v27, v32, v33
	v_cvt_pk_bf16_f32 v28, v34, v35
	v_cvt_pk_bf16_f32 v29, v36, v37
	global_store_dwordx4 v[100:101], v[26:29], off offset:256
	s_waitcnt vmcnt(10)
	s_nop 1
	v_mov_b32_e32 v26, v194
	v_mov_b32_e32 v27, v195
	v_mov_b32_e32 v28, v196
	v_mov_b32_e32 v29, v197
	v_mov_b32_e32 v30, v198
	v_mov_b32_e32 v31, v199
	v_mov_b32_e32 v32, v200
	v_mov_b32_e32 v33, v201
	v_lshlrev_b32_e32 v34, 16, v26
	v_and_b32_e32 v35, 0xffff0000, v26
	v_lshlrev_b32_e32 v36, 16, v30
	v_and_b32_e32 v37, 0xffff0000, v30
	v_lshlrev_b32_e32 v26, 16, v27
	v_and_b32_e32 v27, 0xffff0000, v27
	v_lshlrev_b32_e32 v30, 16, v31
	v_and_b32_e32 v31, 0xffff0000, v31
	v_pk_fma_f32 v[24:25], v[24:25], v[26:27], v[30:31]
	v_lshlrev_b32_e32 v26, 16, v28
	v_and_b32_e32 v27, 0xffff0000, v28
	v_lshlrev_b32_e32 v30, 16, v32
	v_and_b32_e32 v31, 0xffff0000, v32
	v_pk_fma_f32 v[26:27], v[18:19], v[26:27], v[30:31]
	v_lshlrev_b32_e32 v18, 16, v29
	v_and_b32_e32 v19, 0xffff0000, v29
	v_lshlrev_b32_e32 v28, 16, v33
	v_and_b32_e32 v29, 0xffff0000, v33
	v_pk_fma_f32 v[22:23], v[22:23], v[34:35], v[36:37]
	v_pk_fma_f32 v[28:29], v[20:21], v[18:19], v[28:29]
	v_cvt_pk_bf16_f32 v18, v22, v23
	v_cvt_pk_bf16_f32 v19, v24, v25
	v_cvt_pk_bf16_f32 v20, v26, v27
	v_cvt_pk_bf16_f32 v21, v28, v29
	global_store_dwordx4 v[92:93], v[18:21], off offset:256
	s_waitcnt vmcnt(8)
	s_nop 1
	v_mov_b32_e32 v18, v202
	v_mov_b32_e32 v19, v203
	v_mov_b32_e32 v20, v204
	v_mov_b32_e32 v21, v205
	v_mov_b32_e32 v22, v206
	v_mov_b32_e32 v23, v207
	v_mov_b32_e32 v24, v208
	v_mov_b32_e32 v25, v209
	v_lshlrev_b32_e32 v26, 16, v18
	v_and_b32_e32 v27, 0xffff0000, v18
	v_lshlrev_b32_e32 v28, 16, v22
	v_and_b32_e32 v29, 0xffff0000, v22
	v_lshlrev_b32_e32 v18, 16, v19
	v_and_b32_e32 v19, 0xffff0000, v19
	v_lshlrev_b32_e32 v22, 16, v23
	v_and_b32_e32 v23, 0xffff0000, v23
	v_pk_fma_f32 v[16:17], v[16:17], v[18:19], v[22:23]
	v_lshlrev_b32_e32 v18, 16, v20
	v_and_b32_e32 v19, 0xffff0000, v20
	v_lshlrev_b32_e32 v22, 16, v24
	v_and_b32_e32 v23, 0xffff0000, v24
	v_pk_fma_f32 v[18:19], v[10:11], v[18:19], v[22:23]
	v_lshlrev_b32_e32 v10, 16, v21
	v_and_b32_e32 v11, 0xffff0000, v21
	v_lshlrev_b32_e32 v20, 16, v25
	v_and_b32_e32 v21, 0xffff0000, v25
	v_pk_fma_f32 v[14:15], v[14:15], v[26:27], v[28:29]
	v_pk_fma_f32 v[20:21], v[12:13], v[10:11], v[20:21]
	v_cvt_pk_bf16_f32 v10, v14, v15
	v_cvt_pk_bf16_f32 v11, v16, v17
	v_cvt_pk_bf16_f32 v12, v18, v19
	v_cvt_pk_bf16_f32 v13, v20, v21
	global_store_dwordx4 v[84:85], v[10:13], off offset:256
	s_waitcnt vmcnt(6)
	s_nop 1
	v_mov_b32_e32 v10, v210
	v_mov_b32_e32 v11, v211
	v_mov_b32_e32 v12, v212
	v_mov_b32_e32 v13, v213
	v_mov_b32_e32 v14, v214
	v_mov_b32_e32 v15, v215
	v_mov_b32_e32 v16, v216
	v_mov_b32_e32 v17, v217
	v_lshlrev_b32_e32 v18, 16, v10
	v_and_b32_e32 v19, 0xffff0000, v10
	v_lshlrev_b32_e32 v20, 16, v14
	v_and_b32_e32 v21, 0xffff0000, v14
	v_lshlrev_b32_e32 v10, 16, v11
	v_and_b32_e32 v11, 0xffff0000, v11
	v_lshlrev_b32_e32 v14, 16, v15
	v_and_b32_e32 v15, 0xffff0000, v15
	v_pk_fma_f32 v[8:9], v[8:9], v[10:11], v[14:15]
	v_lshlrev_b32_e32 v10, 16, v12
	v_and_b32_e32 v11, 0xffff0000, v12
	v_lshlrev_b32_e32 v14, 16, v16
	v_and_b32_e32 v15, 0xffff0000, v16
	v_pk_fma_f32 v[10:11], v[0:1], v[10:11], v[14:15]
	v_lshlrev_b32_e32 v0, 16, v13
	v_and_b32_e32 v1, 0xffff0000, v13
	v_lshlrev_b32_e32 v12, 16, v17
	v_and_b32_e32 v13, 0xffff0000, v17
	v_pk_fma_f32 v[6:7], v[6:7], v[18:19], v[20:21]
	v_pk_fma_f32 v[12:13], v[2:3], v[0:1], v[12:13]
	v_cvt_pk_bf16_f32 v0, v6, v7
	v_cvt_pk_bf16_f32 v1, v8, v9
	v_cvt_pk_bf16_f32 v2, v10, v11
	v_cvt_pk_bf16_f32 v3, v12, v13
	s_mov_b64 s[0:1], -1
	global_store_dwordx4 v[76:77], v[0:3], off offset:256
	s_cbranch_vccnz .LBB0_218
	s_andn2_b64 vcc, exec, s[42:43]
	s_cbranch_vccnz .LBB0_217
	s_barrier
	s_branch .LBB0_217
